# v40 + grid-barrier spin loops poll without s_sleep
# baseline (speedup 1.0000x reference)
; __global__ void __launch_bounds__(NTHREADS, 2) mega_fwd(Args a) {
;     ...
;     if (hi > 1000) grid.sync();
.LBB0_14:
	s_nop 0
	global_load_dword v2, v0, s[6:7] offset:32 sc1
	s_waitcnt vmcnt(0)
	v_and_b32_e32 v2, 0xffff0000, v2
	v_cmp_ne_u32_e32 vcc, v2, v1
	s_or_b64 s[34:35], vcc, s[34:35]
	s_andn2_b64 exec, exec, s[34:35]
	s_cbranch_execnz .LBB0_14

; __device__ __forceinline__ unsigned xb_ld(unsigned* p)              { return __hip_atomic_load(p, __ATOMIC_RELAXED, __HIP_MEMORY_SCOPE_AGENT); }
; __device__ __forceinline__ void xcd_barrier_complete(unsigned* bar, unsigned x, unsigned& nloc, unsigned& nx) {
;     ...
;     for (;;) {
;         sum = 0u; cnt = 0u; mine = 0u;
; #pragma unroll
;         for (unsigned j = 0; j < 16; ++j) { const unsigned c = xb_ld(&bar[XB_XCNT(j)]); sum += c; cnt += (c > 0u) ? 1u : 0u; mine = (j == x) ? c : mine; }
;         if (sum == G) break;
;         __builtin_amdgcn_s_sleep(1);
;         if ((++sp & 255u) == 0u) { if (xb_ld(&bar[XB_TMO])) break; if (sp > XB_SPIN_CAP) { atomicAdd(&bar[XB_TMO], 1u); break; } }
.LBB0_120:
	global_load_dword v15, v16, s[6:7] sc1
	s_waitcnt lgkmcnt(0)
	global_load_dword v0, v16, s[16:17] sc1
	global_load_dword v1, v16, s[18:19] sc1
	global_load_dword v2, v16, s[36:37] sc1
	global_load_dword v3, v16, s[40:41] sc1
	global_load_dword v4, v16, s[42:43] sc1
	global_load_dword v5, v16, s[48:49] sc1
	global_load_dword v6, v16, s[50:51] sc1
	global_load_dword v7, v16, s[52:53] sc1
	global_load_dword v8, v16, s[54:55] sc1
	global_load_dword v9, v16, s[56:57] sc1
	global_load_dword v10, v16, s[66:67] sc1
	global_load_dword v11, v16, s[68:69] sc1
	global_load_dword v12, v16, s[70:71] sc1
	global_load_dword v13, v16, s[72:73] sc1
	global_load_dword v14, v16, s[74:75] sc1
	s_mov_b64 s[76:77], -1
	s_mov_b64 s[78:79], -1
	s_waitcnt vmcnt(14)
	v_add_u32_e32 v17, v0, v15
	s_waitcnt vmcnt(13)
	v_add_u32_e32 v17, v17, v1
	s_waitcnt vmcnt(12)
	v_add_u32_e32 v17, v17, v2
	s_waitcnt vmcnt(11)
	v_add_u32_e32 v17, v17, v3
	s_waitcnt vmcnt(10)
	v_add_u32_e32 v17, v17, v4
	s_waitcnt vmcnt(9)
	v_add_u32_e32 v17, v17, v5
	s_waitcnt vmcnt(8)
	v_add_u32_e32 v17, v17, v6
	s_waitcnt vmcnt(7)
	v_add_u32_e32 v17, v17, v7
	s_waitcnt vmcnt(6)
	v_add_u32_e32 v17, v17, v8
	s_waitcnt vmcnt(5)
	v_add_u32_e32 v17, v17, v9
	s_waitcnt vmcnt(4)
	v_add_u32_e32 v17, v17, v10
	s_waitcnt vmcnt(3)
	v_add_u32_e32 v17, v17, v11
	s_waitcnt vmcnt(2)
	v_add_u32_e32 v17, v17, v12
	s_waitcnt vmcnt(1)
	v_add_u32_e32 v17, v17, v13
	s_waitcnt vmcnt(0)
	v_add_u32_e32 v17, v17, v14
	v_cmp_eq_u32_e32 vcc, s3, v17
	s_cbranch_vccnz .LBB0_119
	s_and_b32 s9, s8, 0xff
	s_cmp_eq_u32 s9, 0
	s_mov_b64 s[80:81], -1
	s_nop 0
	s_cbranch_scc1 .LBB0_124
	s_and_b64 vcc, exec, s[80:81]
	s_cbranch_vccz .LBB0_119

; __device__ __forceinline__ unsigned xb_ld(unsigned* p)              { return __hip_atomic_load(p, __ATOMIC_RELAXED, __HIP_MEMORY_SCOPE_AGENT); }
; #define XB_SPIN(cond, bar) do { unsigned _sp = 0; while (cond) { __builtin_amdgcn_s_sleep(1); \
;     if ((++_sp & 255u) == 0u) { if (xb_ld(&(bar)[XB_TMO])) break; if (_sp > XB_SPIN_CAP) { atomicAdd(&(bar)[XB_TMO], 1u); break; } } } } while (0)
; __device__ __forceinline__ void xcd_barrier(const XcdBarrier& b) {
;     ...
;             else XB_SPIN(xb_ld(&bar[XB_TOPGEN]) == tg, bar);
.LBB0_138:
	s_and_b32 s8, s3, 0xff
	s_mov_b64 s[48:49], -1
	s_cmp_lg_u32 s8, 0
	s_mov_b64 s[52:53], -1
	s_nop 0
	s_cbranch_scc0 .LBB0_141
	s_and_b64 vcc, exec, s[52:53]
	s_cbranch_vccz .LBB0_137

; __device__ __forceinline__ unsigned xb_ld(unsigned* p)              { return __hip_atomic_load(p, __ATOMIC_RELAXED, __HIP_MEMORY_SCOPE_AGENT); }
; #define XB_SPIN(cond, bar) do { unsigned _sp = 0; while (cond) { __builtin_amdgcn_s_sleep(1); \
;     if ((++_sp & 255u) == 0u) { if (xb_ld(&(bar)[XB_TMO])) break; if (_sp > XB_SPIN_CAP) { atomicAdd(&(bar)[XB_TMO], 1u); break; } } } } while (0)
; __device__ __forceinline__ void xcd_barrier(const XcdBarrier& b) {
;     ...
;             XB_SPIN(xb_ld(&bar[XB_XGEN(b.x)]) == gen, bar);
.LBB0_155:
	s_and_b32 s8, s3, 0xff
	s_cmp_lg_u32 s8, 0
	s_mov_b64 s[50:51], -1
	s_nop 0
	s_cbranch_scc0 .LBB0_158
	s_mov_b64 s[52:53], -1
	s_and_b64 vcc, exec, s[50:51]
	s_cbranch_vccz .LBB0_154

; __device__ __forceinline__ unsigned xb_ld(unsigned* p)              { return __hip_atomic_load(p, __ATOMIC_RELAXED, __HIP_MEMORY_SCOPE_AGENT); }
; __device__ __forceinline__ void xcd_barrier_complete(unsigned* bar, unsigned x, unsigned& nloc, unsigned& nx) {
;     ...
;     for (;;) {
;         sum = 0u; cnt = 0u; mine = 0u;
; #pragma unroll
;         for (unsigned j = 0; j < 16; ++j) { const unsigned c = xb_ld(&bar[XB_XCNT(j)]); sum += c; cnt += (c > 0u) ? 1u : 0u; mine = (j == x) ? c : mine; }
;         if (sum == G) break;
;         __builtin_amdgcn_s_sleep(1);
;         if ((++sp & 255u) == 0u) { if (xb_ld(&bar[XB_TMO])) break; if (sp > XB_SPIN_CAP) { atomicAdd(&bar[XB_TMO], 1u); break; } }
.LBB0_191:
	global_load_dword v15, v16, s[6:7] sc1
	s_waitcnt lgkmcnt(0)
	global_load_dword v0, v16, s[16:17] sc1
	global_load_dword v1, v16, s[18:19] sc1
	global_load_dword v2, v16, s[36:37] sc1
	global_load_dword v3, v16, s[42:43] sc1
	global_load_dword v4, v16, s[48:49] sc1
	global_load_dword v5, v16, s[50:51] sc1
	global_load_dword v6, v16, s[52:53] sc1
	global_load_dword v7, v16, s[54:55] sc1
	global_load_dword v8, v16, s[56:57] sc1
	global_load_dword v9, v16, s[66:67] sc1
	global_load_dword v10, v16, s[68:69] sc1
	global_load_dword v11, v16, s[70:71] sc1
	global_load_dword v12, v16, s[72:73] sc1
	global_load_dword v13, v16, s[74:75] sc1
	global_load_dword v14, v16, s[76:77] sc1
	s_mov_b64 s[78:79], -1
	s_mov_b64 s[80:81], -1
	s_waitcnt vmcnt(14)
	v_add_u32_e32 v17, v0, v15
	s_waitcnt vmcnt(13)
	v_add_u32_e32 v17, v17, v1
	s_waitcnt vmcnt(12)
	v_add_u32_e32 v17, v17, v2
	s_waitcnt vmcnt(11)
	v_add_u32_e32 v17, v17, v3
	s_waitcnt vmcnt(10)
	v_add_u32_e32 v17, v17, v4
	s_waitcnt vmcnt(9)
	v_add_u32_e32 v17, v17, v5
	s_waitcnt vmcnt(8)
	v_add_u32_e32 v17, v17, v6
	s_waitcnt vmcnt(7)
	v_add_u32_e32 v17, v17, v7
	s_waitcnt vmcnt(6)
	v_add_u32_e32 v17, v17, v8
	s_waitcnt vmcnt(5)
	v_add_u32_e32 v17, v17, v9
	s_waitcnt vmcnt(4)
	v_add_u32_e32 v17, v17, v10
	s_waitcnt vmcnt(3)
	v_add_u32_e32 v17, v17, v11
	s_waitcnt vmcnt(2)
	v_add_u32_e32 v17, v17, v12
	s_waitcnt vmcnt(1)
	v_add_u32_e32 v17, v17, v13
	s_waitcnt vmcnt(0)
	v_add_u32_e32 v17, v17, v14
	v_cmp_eq_u32_e32 vcc, s3, v17
	s_cbranch_vccnz .LBB0_190
	s_and_b32 s9, s8, 0xff
	s_cmp_eq_u32 s9, 0
	s_mov_b64 s[82:83], -1
	s_nop 0
	s_cbranch_scc1 .LBB0_195
	s_and_b64 vcc, exec, s[82:83]
	s_cbranch_vccz .LBB0_190

; __device__ __forceinline__ unsigned xb_ld(unsigned* p)              { return __hip_atomic_load(p, __ATOMIC_RELAXED, __HIP_MEMORY_SCOPE_AGENT); }
; #define XB_SPIN(cond, bar) do { unsigned _sp = 0; while (cond) { __builtin_amdgcn_s_sleep(1); \
;     if ((++_sp & 255u) == 0u) { if (xb_ld(&(bar)[XB_TMO])) break; if (_sp > XB_SPIN_CAP) { atomicAdd(&(bar)[XB_TMO], 1u); break; } } } } while (0)
; __device__ __forceinline__ void xcd_barrier(const XcdBarrier& b) {
;     ...
;             else XB_SPIN(xb_ld(&bar[XB_TOPGEN]) == tg, bar);
.LBB0_209:
	s_and_b32 s8, s3, 0xff
	s_mov_b64 s[50:51], -1
	s_cmp_lg_u32 s8, 0
	s_mov_b64 s[54:55], -1
	s_nop 0
	s_cbranch_scc0 .LBB0_212
	s_and_b64 vcc, exec, s[54:55]
	s_cbranch_vccz .LBB0_208

; __device__ __forceinline__ unsigned xb_ld(unsigned* p)              { return __hip_atomic_load(p, __ATOMIC_RELAXED, __HIP_MEMORY_SCOPE_AGENT); }
; #define XB_SPIN(cond, bar) do { unsigned _sp = 0; while (cond) { __builtin_amdgcn_s_sleep(1); \
;     if ((++_sp & 255u) == 0u) { if (xb_ld(&(bar)[XB_TMO])) break; if (_sp > XB_SPIN_CAP) { atomicAdd(&(bar)[XB_TMO], 1u); break; } } } } while (0)
; __device__ __forceinline__ void xcd_barrier(const XcdBarrier& b) {
;     ...
;             XB_SPIN(xb_ld(&bar[XB_XGEN(b.x)]) == gen, bar);
.LBB0_226:
	s_and_b32 s8, s3, 0xff
	s_cmp_lg_u32 s8, 0
	s_mov_b64 s[52:53], -1
	s_nop 0
	s_cbranch_scc0 .LBB0_229
	s_mov_b64 s[54:55], -1
	s_and_b64 vcc, exec, s[52:53]
	s_cbranch_vccz .LBB0_225

; __device__ __forceinline__ unsigned xb_ld(unsigned* p)              { return __hip_atomic_load(p, __ATOMIC_RELAXED, __HIP_MEMORY_SCOPE_AGENT); }
; __device__ __forceinline__ void xcd_barrier_complete(unsigned* bar, unsigned x, unsigned& nloc, unsigned& nx) {
;     ...
;     for (;;) {
;         sum = 0u; cnt = 0u; mine = 0u;
; #pragma unroll
;         for (unsigned j = 0; j < 16; ++j) { const unsigned c = xb_ld(&bar[XB_XCNT(j)]); sum += c; cnt += (c > 0u) ? 1u : 0u; mine = (j == x) ? c : mine; }
;         if (sum == G) break;
;         __builtin_amdgcn_s_sleep(1);
;         if ((++sp & 255u) == 0u) { if (xb_ld(&bar[XB_TMO])) break; if (sp > XB_SPIN_CAP) { atomicAdd(&bar[XB_TMO], 1u); break; } }
.LBB0_308:
	global_load_dword v15, v16, s[6:7] sc1
	s_waitcnt lgkmcnt(0)
	global_load_dword v0, v16, s[16:17] sc1
	global_load_dword v1, v16, s[18:19] sc1
	global_load_dword v2, v16, s[38:39] sc1
	global_load_dword v3, v16, s[42:43] sc1
	global_load_dword v4, v16, s[48:49] sc1
	global_load_dword v5, v16, s[50:51] sc1
	global_load_dword v6, v16, s[52:53] sc1
	global_load_dword v7, v16, s[54:55] sc1
	global_load_dword v8, v16, s[56:57] sc1
	global_load_dword v9, v16, s[66:67] sc1
	global_load_dword v10, v16, s[68:69] sc1
	global_load_dword v11, v16, s[70:71] sc1
	global_load_dword v12, v16, s[72:73] sc1
	global_load_dword v13, v16, s[74:75] sc1
	global_load_dword v14, v16, s[76:77] sc1
	s_mov_b64 s[78:79], -1
	s_mov_b64 s[80:81], -1
	s_waitcnt vmcnt(14)
	v_add_u32_e32 v17, v0, v15
	s_waitcnt vmcnt(13)
	v_add_u32_e32 v17, v17, v1
	s_waitcnt vmcnt(12)
	v_add_u32_e32 v17, v17, v2
	s_waitcnt vmcnt(11)
	v_add_u32_e32 v17, v17, v3
	s_waitcnt vmcnt(10)
	v_add_u32_e32 v17, v17, v4
	s_waitcnt vmcnt(9)
	v_add_u32_e32 v17, v17, v5
	s_waitcnt vmcnt(8)
	v_add_u32_e32 v17, v17, v6
	s_waitcnt vmcnt(7)
	v_add_u32_e32 v17, v17, v7
	s_waitcnt vmcnt(6)
	v_add_u32_e32 v17, v17, v8
	s_waitcnt vmcnt(5)
	v_add_u32_e32 v17, v17, v9
	s_waitcnt vmcnt(4)
	v_add_u32_e32 v17, v17, v10
	s_waitcnt vmcnt(3)
	v_add_u32_e32 v17, v17, v11
	s_waitcnt vmcnt(2)
	v_add_u32_e32 v17, v17, v12
	s_waitcnt vmcnt(1)
	v_add_u32_e32 v17, v17, v13
	s_waitcnt vmcnt(0)
	v_add_u32_e32 v17, v17, v14
	v_cmp_eq_u32_e32 vcc, s3, v17
	s_cbranch_vccnz .LBB0_307
	s_and_b32 s9, s8, 0xff
	s_cmp_eq_u32 s9, 0
	s_mov_b64 s[82:83], -1
	s_nop 0
	s_cbranch_scc1 .LBB0_312
	s_and_b64 vcc, exec, s[82:83]
	s_cbranch_vccz .LBB0_307

; __device__ __forceinline__ unsigned xb_ld(unsigned* p)              { return __hip_atomic_load(p, __ATOMIC_RELAXED, __HIP_MEMORY_SCOPE_AGENT); }
; __device__ __forceinline__ void xcd_barrier_complete(unsigned* bar, unsigned x, unsigned& nloc, unsigned& nx) {
;     ...
;     for (;;) {
;         sum = 0u; cnt = 0u; mine = 0u;
; #pragma unroll
;         for (unsigned j = 0; j < 16; ++j) { const unsigned c = xb_ld(&bar[XB_XCNT(j)]); sum += c; cnt += (c > 0u) ? 1u : 0u; mine = (j == x) ? c : mine; }
;         if (sum == G) break;
;         __builtin_amdgcn_s_sleep(1);
;         if ((++sp & 255u) == 0u) { if (xb_ld(&bar[XB_TMO])) break; if (sp > XB_SPIN_CAP) { atomicAdd(&bar[XB_TMO], 1u); break; } }
.LBB0_498:
	global_load_dword v15, v16, s[6:7] sc1
	s_waitcnt lgkmcnt(0)
	global_load_dword v0, v16, s[12:13] sc1
	global_load_dword v1, v16, s[14:15] sc1
	global_load_dword v2, v16, s[18:19] sc1
	global_load_dword v3, v16, s[38:39] sc1
	global_load_dword v4, v16, s[42:43] sc1
	global_load_dword v5, v16, s[48:49] sc1
	global_load_dword v6, v16, s[50:51] sc1
	global_load_dword v7, v16, s[52:53] sc1
	global_load_dword v8, v16, s[54:55] sc1
	global_load_dword v9, v16, s[56:57] sc1
	global_load_dword v10, v16, s[66:67] sc1
	global_load_dword v11, v16, s[68:69] sc1
	global_load_dword v12, v16, s[70:71] sc1
	global_load_dword v13, v16, s[72:73] sc1
	global_load_dword v14, v16, s[74:75] sc1
	s_mov_b64 s[76:77], -1
	s_mov_b64 s[78:79], -1
	s_waitcnt vmcnt(14)
	v_add_u32_e32 v17, v0, v15
	s_waitcnt vmcnt(13)
	v_add_u32_e32 v17, v17, v1
	s_waitcnt vmcnt(12)
	v_add_u32_e32 v17, v17, v2
	s_waitcnt vmcnt(11)
	v_add_u32_e32 v17, v17, v3
	s_waitcnt vmcnt(10)
	v_add_u32_e32 v17, v17, v4
	s_waitcnt vmcnt(9)
	v_add_u32_e32 v17, v17, v5
	s_waitcnt vmcnt(8)
	v_add_u32_e32 v17, v17, v6
	s_waitcnt vmcnt(7)
	v_add_u32_e32 v17, v17, v7
	s_waitcnt vmcnt(6)
	v_add_u32_e32 v17, v17, v8
	s_waitcnt vmcnt(5)
	v_add_u32_e32 v17, v17, v9
	s_waitcnt vmcnt(4)
	v_add_u32_e32 v17, v17, v10
	s_waitcnt vmcnt(3)
	v_add_u32_e32 v17, v17, v11
	s_waitcnt vmcnt(2)
	v_add_u32_e32 v17, v17, v12
	s_waitcnt vmcnt(1)
	v_add_u32_e32 v17, v17, v13
	s_waitcnt vmcnt(0)
	v_add_u32_e32 v17, v17, v14
	v_cmp_eq_u32_e32 vcc, s3, v17
	s_cbranch_vccnz .LBB0_497
	s_and_b32 s9, s8, 0xff
	s_cmp_eq_u32 s9, 0
	s_mov_b64 s[80:81], -1
	s_nop 0
	s_cbranch_scc1 .LBB0_502
	s_and_b64 vcc, exec, s[80:81]
	s_cbranch_vccz .LBB0_497

; __device__ __forceinline__ unsigned xb_ld(unsigned* p)              { return __hip_atomic_load(p, __ATOMIC_RELAXED, __HIP_MEMORY_SCOPE_AGENT); }
; __device__ __forceinline__ void xcd_barrier_complete(unsigned* bar, unsigned x, unsigned& nloc, unsigned& nx) {
;     ...
;     for (;;) {
;         sum = 0u; cnt = 0u; mine = 0u;
; #pragma unroll
;         for (unsigned j = 0; j < 16; ++j) { const unsigned c = xb_ld(&bar[XB_XCNT(j)]); sum += c; cnt += (c > 0u) ? 1u : 0u; mine = (j == x) ? c : mine; }
;         if (sum == G) break;
;         __builtin_amdgcn_s_sleep(1);
;         if ((++sp & 255u) == 0u) { if (xb_ld(&bar[XB_TMO])) break; if (sp > XB_SPIN_CAP) { atomicAdd(&bar[XB_TMO], 1u); break; } }
.LBB0_676:
	global_load_dword v15, v16, s[6:7] sc1
	s_waitcnt lgkmcnt(0)
	global_load_dword v0, v16, s[12:13] sc1
	global_load_dword v1, v16, s[14:15] sc1
	global_load_dword v2, v16, s[18:19] sc1
	global_load_dword v3, v16, s[38:39] sc1
	global_load_dword v4, v16, s[42:43] sc1
	global_load_dword v5, v16, s[48:49] sc1
	global_load_dword v6, v16, s[50:51] sc1
	global_load_dword v7, v16, s[52:53] sc1
	global_load_dword v8, v16, s[54:55] sc1
	global_load_dword v9, v16, s[56:57] sc1
	global_load_dword v10, v16, s[64:65] sc1
	global_load_dword v11, v16, s[66:67] sc1
	global_load_dword v12, v16, s[68:69] sc1
	global_load_dword v13, v16, s[70:71] sc1
	global_load_dword v14, v16, s[72:73] sc1
	s_mov_b64 s[74:75], -1
	s_mov_b64 s[76:77], -1
	s_waitcnt vmcnt(14)
	v_add_u32_e32 v17, v0, v15
	s_waitcnt vmcnt(13)
	v_add_u32_e32 v17, v17, v1
	s_waitcnt vmcnt(12)
	v_add_u32_e32 v17, v17, v2
	s_waitcnt vmcnt(11)
	v_add_u32_e32 v17, v17, v3
	s_waitcnt vmcnt(10)
	v_add_u32_e32 v17, v17, v4
	s_waitcnt vmcnt(9)
	v_add_u32_e32 v17, v17, v5
	s_waitcnt vmcnt(8)
	v_add_u32_e32 v17, v17, v6
	s_waitcnt vmcnt(7)
	v_add_u32_e32 v17, v17, v7
	s_waitcnt vmcnt(6)
	v_add_u32_e32 v17, v17, v8
	s_waitcnt vmcnt(5)
	v_add_u32_e32 v17, v17, v9
	s_waitcnt vmcnt(4)
	v_add_u32_e32 v17, v17, v10
	s_waitcnt vmcnt(3)
	v_add_u32_e32 v17, v17, v11
	s_waitcnt vmcnt(2)
	v_add_u32_e32 v17, v17, v12
	s_waitcnt vmcnt(1)
	v_add_u32_e32 v17, v17, v13
	s_waitcnt vmcnt(0)
	v_add_u32_e32 v17, v17, v14
	v_cmp_eq_u32_e32 vcc, s3, v17
	s_cbranch_vccnz .LBB0_675
	s_and_b32 s9, s8, 0xff
	s_cmp_eq_u32 s9, 0
	s_mov_b64 s[78:79], -1
	s_nop 0
	s_cbranch_scc1 .LBB0_680
	s_and_b64 vcc, exec, s[78:79]
	s_cbranch_vccz .LBB0_675

; __device__ __forceinline__ unsigned xb_ld(unsigned* p)              { return __hip_atomic_load(p, __ATOMIC_RELAXED, __HIP_MEMORY_SCOPE_AGENT); }
; __device__ __forceinline__ void xcd_barrier_complete(unsigned* bar, unsigned x, unsigned& nloc, unsigned& nx) {
;     ...
;     for (;;) {
;         sum = 0u; cnt = 0u; mine = 0u;
; #pragma unroll
;         for (unsigned j = 0; j < 16; ++j) { const unsigned c = xb_ld(&bar[XB_XCNT(j)]); sum += c; cnt += (c > 0u) ? 1u : 0u; mine = (j == x) ? c : mine; }
;         if (sum == G) break;
;         __builtin_amdgcn_s_sleep(1);
;         if ((++sp & 255u) == 0u) { if (xb_ld(&bar[XB_TMO])) break; if (sp > XB_SPIN_CAP) { atomicAdd(&bar[XB_TMO], 1u); break; } }
.LBB0_867:
	global_load_dword v15, v16, s[6:7] sc1
	s_waitcnt lgkmcnt(0)
	global_load_dword v0, v16, s[12:13] sc1
	global_load_dword v1, v16, s[14:15] sc1
	global_load_dword v2, v16, s[18:19] sc1
	global_load_dword v3, v16, s[20:21] sc1
	global_load_dword v4, v16, s[38:39] sc1
	global_load_dword v5, v16, s[42:43] sc1
	global_load_dword v6, v16, s[48:49] sc1
	global_load_dword v7, v16, s[50:51] sc1
	global_load_dword v8, v16, s[52:53] sc1
	global_load_dword v9, v16, s[54:55] sc1
	global_load_dword v10, v16, s[56:57] sc1
	global_load_dword v11, v16, s[64:65] sc1
	global_load_dword v12, v16, s[66:67] sc1
	global_load_dword v13, v16, s[68:69] sc1
	global_load_dword v14, v16, s[70:71] sc1
	s_mov_b64 s[72:73], -1
	s_mov_b64 s[74:75], -1
	s_waitcnt vmcnt(14)
	v_add_u32_e32 v17, v0, v15
	s_waitcnt vmcnt(13)
	v_add_u32_e32 v17, v17, v1
	s_waitcnt vmcnt(12)
	v_add_u32_e32 v17, v17, v2
	s_waitcnt vmcnt(11)
	v_add_u32_e32 v17, v17, v3
	s_waitcnt vmcnt(10)
	v_add_u32_e32 v17, v17, v4
	s_waitcnt vmcnt(9)
	v_add_u32_e32 v17, v17, v5
	s_waitcnt vmcnt(8)
	v_add_u32_e32 v17, v17, v6
	s_waitcnt vmcnt(7)
	v_add_u32_e32 v17, v17, v7
	s_waitcnt vmcnt(6)
	v_add_u32_e32 v17, v17, v8
	s_waitcnt vmcnt(5)
	v_add_u32_e32 v17, v17, v9
	s_waitcnt vmcnt(4)
	v_add_u32_e32 v17, v17, v10
	s_waitcnt vmcnt(3)
	v_add_u32_e32 v17, v17, v11
	s_waitcnt vmcnt(2)
	v_add_u32_e32 v17, v17, v12
	s_waitcnt vmcnt(1)
	v_add_u32_e32 v17, v17, v13
	s_waitcnt vmcnt(0)
	v_add_u32_e32 v17, v17, v14
	v_cmp_eq_u32_e32 vcc, s3, v17
	s_cbranch_vccnz .LBB0_866
	s_and_b32 s9, s8, 0xff
	s_cmp_eq_u32 s9, 0
	s_mov_b64 s[76:77], -1
	s_nop 0
	s_cbranch_scc1 .LBB0_871
	s_and_b64 vcc, exec, s[76:77]
	s_cbranch_vccz .LBB0_866

; __device__ __forceinline__ unsigned xb_ld(unsigned* p)              { return __hip_atomic_load(p, __ATOMIC_RELAXED, __HIP_MEMORY_SCOPE_AGENT); }
; #define XB_SPIN(cond, bar) do { unsigned _sp = 0; while (cond) { __builtin_amdgcn_s_sleep(1); \
;     if ((++_sp & 255u) == 0u) { if (xb_ld(&(bar)[XB_TMO])) break; if (_sp > XB_SPIN_CAP) { atomicAdd(&(bar)[XB_TMO], 1u); break; } } } } while (0)
; __device__ __forceinline__ void xcd_barrier(const XcdBarrier& b) {
;     ...
;             else XB_SPIN(xb_ld(&bar[XB_TOPGEN]) == tg, bar);
.LBB0_885:
	s_and_b32 s8, s3, 0xff
	s_mov_b64 s[42:43], -1
	s_cmp_lg_u32 s8, 0
	s_mov_b64 s[50:51], -1
	s_nop 0
	s_cbranch_scc0 .LBB0_888
	s_and_b64 vcc, exec, s[50:51]
	s_cbranch_vccz .LBB0_884

; __device__ __forceinline__ unsigned xb_ld(unsigned* p)              { return __hip_atomic_load(p, __ATOMIC_RELAXED, __HIP_MEMORY_SCOPE_AGENT); }
; #define XB_SPIN(cond, bar) do { unsigned _sp = 0; while (cond) { __builtin_amdgcn_s_sleep(1); \
;     if ((++_sp & 255u) == 0u) { if (xb_ld(&(bar)[XB_TMO])) break; if (_sp > XB_SPIN_CAP) { atomicAdd(&(bar)[XB_TMO], 1u); break; } } } } while (0)
; __device__ __forceinline__ void xcd_barrier(const XcdBarrier& b) {
;     ...
;             XB_SPIN(xb_ld(&bar[XB_XGEN(b.x)]) == gen, bar);
.LBB0_902:
	s_and_b32 s8, s3, 0xff
	s_cmp_lg_u32 s8, 0
	s_mov_b64 s[48:49], -1
	s_nop 0
	s_cbranch_scc0 .LBB0_905
	s_mov_b64 s[50:51], -1
	s_and_b64 vcc, exec, s[48:49]
	s_cbranch_vccz .LBB0_901

; __device__ __forceinline__ unsigned xb_ld(unsigned* p)              { return __hip_atomic_load(p, __ATOMIC_RELAXED, __HIP_MEMORY_SCOPE_AGENT); }
; __device__ __forceinline__ void xcd_barrier_complete(unsigned* bar, unsigned x, unsigned& nloc, unsigned& nx) {
;     ...
;     for (;;) {
;         sum = 0u; cnt = 0u; mine = 0u;
; #pragma unroll
;         for (unsigned j = 0; j < 16; ++j) { const unsigned c = xb_ld(&bar[XB_XCNT(j)]); sum += c; cnt += (c > 0u) ? 1u : 0u; mine = (j == x) ? c : mine; }
;         if (sum == G) break;
;         __builtin_amdgcn_s_sleep(1);
;         if ((++sp & 255u) == 0u) { if (xb_ld(&bar[XB_TMO])) break; if (sp > XB_SPIN_CAP) { atomicAdd(&bar[XB_TMO], 1u); break; } }
.LBB0_1032:
	global_load_dword v15, v16, s[6:7] sc1
	s_waitcnt lgkmcnt(0)
	global_load_dword v0, v16, s[12:13] sc1
	global_load_dword v1, v16, s[14:15] sc1
	global_load_dword v2, v16, s[18:19] sc1
	global_load_dword v3, v16, s[20:21] sc1
	global_load_dword v4, v16, s[38:39] sc1
	global_load_dword v5, v16, s[42:43] sc1
	global_load_dword v6, v16, s[44:45] sc1
	global_load_dword v7, v16, s[46:47] sc1
	global_load_dword v8, v16, s[48:49] sc1
	global_load_dword v9, v16, s[50:51] sc1
	global_load_dword v10, v16, s[52:53] sc1
	global_load_dword v11, v16, s[54:55] sc1
	global_load_dword v12, v16, s[56:57] sc1
	global_load_dword v13, v16, s[64:65] sc1
	global_load_dword v14, v16, s[66:67] sc1
	s_mov_b64 s[68:69], -1
	s_mov_b64 s[70:71], -1
	s_waitcnt vmcnt(14)
	v_add_u32_e32 v17, v0, v15
	s_waitcnt vmcnt(13)
	v_add_u32_e32 v17, v17, v1
	s_waitcnt vmcnt(12)
	v_add_u32_e32 v17, v17, v2
	s_waitcnt vmcnt(11)
	v_add_u32_e32 v17, v17, v3
	s_waitcnt vmcnt(10)
	v_add_u32_e32 v17, v17, v4
	s_waitcnt vmcnt(9)
	v_add_u32_e32 v17, v17, v5
	s_waitcnt vmcnt(8)
	v_add_u32_e32 v17, v17, v6
	s_waitcnt vmcnt(7)
	v_add_u32_e32 v17, v17, v7
	s_waitcnt vmcnt(6)
	v_add_u32_e32 v17, v17, v8
	s_waitcnt vmcnt(5)
	v_add_u32_e32 v17, v17, v9
	s_waitcnt vmcnt(4)
	v_add_u32_e32 v17, v17, v10
	s_waitcnt vmcnt(3)
	v_add_u32_e32 v17, v17, v11
	s_waitcnt vmcnt(2)
	v_add_u32_e32 v17, v17, v12
	s_waitcnt vmcnt(1)
	v_add_u32_e32 v17, v17, v13
	s_waitcnt vmcnt(0)
	v_add_u32_e32 v17, v17, v14
	v_cmp_eq_u32_e32 vcc, s3, v17
	s_cbranch_vccnz .LBB0_1031
	s_and_b32 s9, s8, 0xff
	s_cmp_eq_u32 s9, 0
	s_mov_b64 s[72:73], -1
	s_nop 0
	s_cbranch_scc1 .LBB0_1036
	s_and_b64 vcc, exec, s[72:73]
	s_cbranch_vccz .LBB0_1031

; __device__ __forceinline__ unsigned xb_ld(unsigned* p)              { return __hip_atomic_load(p, __ATOMIC_RELAXED, __HIP_MEMORY_SCOPE_AGENT); }
; #define XB_SPIN(cond, bar) do { unsigned _sp = 0; while (cond) { __builtin_amdgcn_s_sleep(1); \
;     if ((++_sp & 255u) == 0u) { if (xb_ld(&(bar)[XB_TMO])) break; if (_sp > XB_SPIN_CAP) { atomicAdd(&(bar)[XB_TMO], 1u); break; } } } } while (0)
; __device__ __forceinline__ void xcd_barrier(const XcdBarrier& b) {
;     ...
;             else XB_SPIN(xb_ld(&bar[XB_TOPGEN]) == tg, bar);
.LBB0_1050:
	s_and_b32 s8, s3, 0xff
	s_mov_b64 s[42:43], -1
	s_cmp_lg_u32 s8, 0
	s_mov_b64 s[46:47], -1
	s_nop 0
	s_cbranch_scc0 .LBB0_1053
	s_and_b64 vcc, exec, s[46:47]
	s_cbranch_vccz .LBB0_1049

; __device__ __forceinline__ unsigned xb_ld(unsigned* p)              { return __hip_atomic_load(p, __ATOMIC_RELAXED, __HIP_MEMORY_SCOPE_AGENT); }
; #define XB_SPIN(cond, bar) do { unsigned _sp = 0; while (cond) { __builtin_amdgcn_s_sleep(1); \
;     if ((++_sp & 255u) == 0u) { if (xb_ld(&(bar)[XB_TMO])) break; if (_sp > XB_SPIN_CAP) { atomicAdd(&(bar)[XB_TMO], 1u); break; } } } } while (0)
; __device__ __forceinline__ void xcd_barrier(const XcdBarrier& b) {
;     ...
;             XB_SPIN(xb_ld(&bar[XB_XGEN(b.x)]) == gen, bar);
.LBB0_1067:
	s_and_b32 s8, s3, 0xff
	s_cmp_lg_u32 s8, 0
	s_mov_b64 s[44:45], -1
	s_nop 0
	s_cbranch_scc0 .LBB0_1070
	s_mov_b64 s[46:47], -1
	s_and_b64 vcc, exec, s[44:45]
	s_cbranch_vccz .LBB0_1066

; __device__ __forceinline__ unsigned xb_ld(unsigned* p)              { return __hip_atomic_load(p, __ATOMIC_RELAXED, __HIP_MEMORY_SCOPE_AGENT); }
; __device__ __forceinline__ void xcd_barrier_complete(unsigned* bar, unsigned x, unsigned& nloc, unsigned& nx) {
;     ...
;     for (;;) {
;         sum = 0u; cnt = 0u; mine = 0u;
; #pragma unroll
;         for (unsigned j = 0; j < 16; ++j) { const unsigned c = xb_ld(&bar[XB_XCNT(j)]); sum += c; cnt += (c > 0u) ? 1u : 0u; mine = (j == x) ? c : mine; }
;         if (sum == G) break;
;         __builtin_amdgcn_s_sleep(1);
;         if ((++sp & 255u) == 0u) { if (xb_ld(&bar[XB_TMO])) break; if (sp > XB_SPIN_CAP) { atomicAdd(&bar[XB_TMO], 1u); break; } }
.LBB0_1278:
	global_load_dword v15, v16, s[6:7] sc1
	s_waitcnt lgkmcnt(0)
	global_load_dword v0, v16, s[12:13] sc1
	global_load_dword v1, v16, s[14:15] sc1
	global_load_dword v2, v16, s[18:19] sc1
	global_load_dword v3, v16, s[20:21] sc1
	global_load_dword v4, v16, s[22:23] sc1
	global_load_dword v5, v16, s[24:25] sc1
	global_load_dword v6, v16, s[38:39] sc1
	global_load_dword v7, v16, s[42:43] sc1
	global_load_dword v8, v16, s[44:45] sc1
	global_load_dword v9, v16, s[46:47] sc1
	global_load_dword v10, v16, s[48:49] sc1
	global_load_dword v11, v16, s[50:51] sc1
	global_load_dword v12, v16, s[52:53] sc1
	global_load_dword v13, v16, s[54:55] sc1
	global_load_dword v14, v16, s[56:57] sc1
	s_mov_b64 s[64:65], -1
	s_mov_b64 s[66:67], -1
	s_waitcnt vmcnt(14)
	v_add_u32_e32 v17, v0, v15
	s_waitcnt vmcnt(13)
	v_add_u32_e32 v17, v17, v1
	s_waitcnt vmcnt(12)
	v_add_u32_e32 v17, v17, v2
	s_waitcnt vmcnt(11)
	v_add_u32_e32 v17, v17, v3
	s_waitcnt vmcnt(10)
	v_add_u32_e32 v17, v17, v4
	s_waitcnt vmcnt(9)
	v_add_u32_e32 v17, v17, v5
	s_waitcnt vmcnt(8)
	v_add_u32_e32 v17, v17, v6
	s_waitcnt vmcnt(7)
	v_add_u32_e32 v17, v17, v7
	s_waitcnt vmcnt(6)
	v_add_u32_e32 v17, v17, v8
	s_waitcnt vmcnt(5)
	v_add_u32_e32 v17, v17, v9
	s_waitcnt vmcnt(4)
	v_add_u32_e32 v17, v17, v10
	s_waitcnt vmcnt(3)
	v_add_u32_e32 v17, v17, v11
	s_waitcnt vmcnt(2)
	v_add_u32_e32 v17, v17, v12
	s_waitcnt vmcnt(1)
	v_add_u32_e32 v17, v17, v13
	s_waitcnt vmcnt(0)
	v_add_u32_e32 v17, v17, v14
	v_cmp_eq_u32_e32 vcc, s3, v17
	s_cbranch_vccnz .LBB0_1277
	s_and_b32 s9, s8, 0xff
	s_cmp_eq_u32 s9, 0
	s_mov_b64 s[68:69], -1
	s_nop 0
	s_cbranch_scc1 .LBB0_1282
	s_and_b64 vcc, exec, s[68:69]
	s_cbranch_vccz .LBB0_1277

; __device__ __forceinline__ unsigned xb_ld(unsigned* p)              { return __hip_atomic_load(p, __ATOMIC_RELAXED, __HIP_MEMORY_SCOPE_AGENT); }
; #define XB_SPIN(cond, bar) do { unsigned _sp = 0; while (cond) { __builtin_amdgcn_s_sleep(1); \
;     if ((++_sp & 255u) == 0u) { if (xb_ld(&(bar)[XB_TMO])) break; if (_sp > XB_SPIN_CAP) { atomicAdd(&(bar)[XB_TMO], 1u); break; } } } } while (0)
; __device__ __forceinline__ void xcd_barrier(const XcdBarrier& b) {
;     ...
;             else XB_SPIN(xb_ld(&bar[XB_TOPGEN]) == tg, bar);
.LBB0_1296:
	s_and_b32 s8, s3, 0xff
	s_mov_b64 s[24:25], -1
	s_cmp_lg_u32 s8, 0
	s_mov_b64 s[42:43], -1
	s_nop 0
	s_cbranch_scc0 .LBB0_1299
	s_and_b64 vcc, exec, s[42:43]
	s_cbranch_vccz .LBB0_1295

; __device__ __forceinline__ unsigned xb_ld(unsigned* p)              { return __hip_atomic_load(p, __ATOMIC_RELAXED, __HIP_MEMORY_SCOPE_AGENT); }
; #define XB_SPIN(cond, bar) do { unsigned _sp = 0; while (cond) { __builtin_amdgcn_s_sleep(1); \
;     if ((++_sp & 255u) == 0u) { if (xb_ld(&(bar)[XB_TMO])) break; if (_sp > XB_SPIN_CAP) { atomicAdd(&(bar)[XB_TMO], 1u); break; } } } } while (0)
; __device__ __forceinline__ void xcd_barrier(const XcdBarrier& b) {
;     ...
;             XB_SPIN(xb_ld(&bar[XB_XGEN(b.x)]) == gen, bar);
.LBB0_1313:
	s_and_b32 s8, s3, 0xff
	s_cmp_lg_u32 s8, 0
	s_mov_b64 s[38:39], -1
	s_nop 0
	s_cbranch_scc0 .LBB0_1316
	s_mov_b64 s[42:43], -1
	s_and_b64 vcc, exec, s[38:39]
	s_cbranch_vccz .LBB0_1312

; __device__ __forceinline__ unsigned xb_ld(unsigned* p)              { return __hip_atomic_load(p, __ATOMIC_RELAXED, __HIP_MEMORY_SCOPE_AGENT); }
; __device__ __forceinline__ void xcd_barrier_complete(unsigned* bar, unsigned x, unsigned& nloc, unsigned& nx) {
;     ...
;     for (;;) {
;         sum = 0u; cnt = 0u; mine = 0u;
; #pragma unroll
;         for (unsigned j = 0; j < 16; ++j) { const unsigned c = xb_ld(&bar[XB_XCNT(j)]); sum += c; cnt += (c > 0u) ? 1u : 0u; mine = (j == x) ? c : mine; }
;         if (sum == G) break;
;         __builtin_amdgcn_s_sleep(1);
;         if ((++sp & 255u) == 0u) { if (xb_ld(&bar[XB_TMO])) break; if (sp > XB_SPIN_CAP) { atomicAdd(&bar[XB_TMO], 1u); break; } }
.LBB0_1456:
	global_load_dword v15, v16, s[6:7] sc1
	s_waitcnt lgkmcnt(0)
	global_load_dword v0, v16, s[12:13] sc1
	global_load_dword v1, v16, s[14:15] sc1
	global_load_dword v2, v16, s[18:19] sc1
	global_load_dword v3, v16, s[20:21] sc1
	global_load_dword v4, v16, s[22:23] sc1
	global_load_dword v5, v16, s[24:25] sc1
	global_load_dword v6, v16, s[38:39] sc1
	global_load_dword v7, v16, s[40:41] sc1
	global_load_dword v8, v16, s[42:43] sc1
	global_load_dword v9, v16, s[44:45] sc1
	global_load_dword v10, v16, s[46:47] sc1
	global_load_dword v11, v16, s[48:49] sc1
	global_load_dword v12, v16, s[50:51] sc1
	global_load_dword v13, v16, s[52:53] sc1
	global_load_dword v14, v16, s[54:55] sc1
	s_mov_b64 s[56:57], -1
	s_mov_b64 s[64:65], -1
	s_waitcnt vmcnt(14)
	v_add_u32_e32 v17, v0, v15
	s_waitcnt vmcnt(13)
	v_add_u32_e32 v17, v17, v1
	s_waitcnt vmcnt(12)
	v_add_u32_e32 v17, v17, v2
	s_waitcnt vmcnt(11)
	v_add_u32_e32 v17, v17, v3
	s_waitcnt vmcnt(10)
	v_add_u32_e32 v17, v17, v4
	s_waitcnt vmcnt(9)
	v_add_u32_e32 v17, v17, v5
	s_waitcnt vmcnt(8)
	v_add_u32_e32 v17, v17, v6
	s_waitcnt vmcnt(7)
	v_add_u32_e32 v17, v17, v7
	s_waitcnt vmcnt(6)
	v_add_u32_e32 v17, v17, v8
	s_waitcnt vmcnt(5)
	v_add_u32_e32 v17, v17, v9
	s_waitcnt vmcnt(4)
	v_add_u32_e32 v17, v17, v10
	s_waitcnt vmcnt(3)
	v_add_u32_e32 v17, v17, v11
	s_waitcnt vmcnt(2)
	v_add_u32_e32 v17, v17, v12
	s_waitcnt vmcnt(1)
	v_add_u32_e32 v17, v17, v13
	s_waitcnt vmcnt(0)
	v_add_u32_e32 v17, v17, v14
	v_cmp_eq_u32_e32 vcc, s3, v17
	s_cbranch_vccnz .LBB0_1455
	s_and_b32 s9, s8, 0xff
	s_cmp_eq_u32 s9, 0
	s_mov_b64 s[66:67], -1
	s_nop 0
	s_cbranch_scc1 .LBB0_1460
	s_and_b64 vcc, exec, s[66:67]
	s_cbranch_vccz .LBB0_1455

; __device__ __forceinline__ unsigned xb_ld(unsigned* p)              { return __hip_atomic_load(p, __ATOMIC_RELAXED, __HIP_MEMORY_SCOPE_AGENT); }
; #define XB_SPIN(cond, bar) do { unsigned _sp = 0; while (cond) { __builtin_amdgcn_s_sleep(1); \
;     if ((++_sp & 255u) == 0u) { if (xb_ld(&(bar)[XB_TMO])) break; if (_sp > XB_SPIN_CAP) { atomicAdd(&(bar)[XB_TMO], 1u); break; } } } } while (0)
; __device__ __forceinline__ void xcd_barrier(const XcdBarrier& b) {
;     ...
;             else XB_SPIN(xb_ld(&bar[XB_TOPGEN]) == tg, bar);
.LBB0_1474:
	s_and_b32 s8, s3, 0xff
	s_mov_b64 s[24:25], -1
	s_cmp_lg_u32 s8, 0
	s_mov_b64 s[40:41], -1
	s_nop 0
	s_cbranch_scc0 .LBB0_1477
	s_and_b64 vcc, exec, s[40:41]
	s_cbranch_vccz .LBB0_1473

; __device__ __forceinline__ unsigned xb_ld(unsigned* p)              { return __hip_atomic_load(p, __ATOMIC_RELAXED, __HIP_MEMORY_SCOPE_AGENT); }
; #define XB_SPIN(cond, bar) do { unsigned _sp = 0; while (cond) { __builtin_amdgcn_s_sleep(1); \
;     if ((++_sp & 255u) == 0u) { if (xb_ld(&(bar)[XB_TMO])) break; if (_sp > XB_SPIN_CAP) { atomicAdd(&(bar)[XB_TMO], 1u); break; } } } } while (0)
; __device__ __forceinline__ void xcd_barrier(const XcdBarrier& b) {
;     ...
;             XB_SPIN(xb_ld(&bar[XB_XGEN(b.x)]) == gen, bar);
.LBB0_1491:
	s_and_b32 s8, s3, 0xff
	s_cmp_lg_u32 s8, 0
	s_mov_b64 s[38:39], -1
	s_nop 0
	s_cbranch_scc0 .LBB0_1494
	s_mov_b64 s[40:41], -1
	s_and_b64 vcc, exec, s[38:39]
	s_cbranch_vccz .LBB0_1490

; __device__ __forceinline__ unsigned xb_ld(unsigned* p)              { return __hip_atomic_load(p, __ATOMIC_RELAXED, __HIP_MEMORY_SCOPE_AGENT); }
; __device__ __forceinline__ void xcd_barrier_complete(unsigned* bar, unsigned x, unsigned& nloc, unsigned& nx) {
;     ...
;     for (;;) {
;         sum = 0u; cnt = 0u; mine = 0u;
; #pragma unroll
;         for (unsigned j = 0; j < 16; ++j) { const unsigned c = xb_ld(&bar[XB_XCNT(j)]); sum += c; cnt += (c > 0u) ? 1u : 0u; mine = (j == x) ? c : mine; }
;         if (sum == G) break;
;         __builtin_amdgcn_s_sleep(1);
;         if ((++sp & 255u) == 0u) { if (xb_ld(&bar[XB_TMO])) break; if (sp > XB_SPIN_CAP) { atomicAdd(&bar[XB_TMO], 1u); break; } }
.LBB0_1550:
	global_load_dword v15, v16, s[6:7] sc1
	s_waitcnt lgkmcnt(0)
	global_load_dword v0, v16, s[8:9] sc1
	global_load_dword v1, v16, s[12:13] sc1
	global_load_dword v2, v16, s[14:15] sc1
	global_load_dword v3, v16, s[18:19] sc1
	global_load_dword v4, v16, s[20:21] sc1
	global_load_dword v5, v16, s[22:23] sc1
	global_load_dword v6, v16, s[24:25] sc1
	global_load_dword v7, v16, s[26:27] sc1
	global_load_dword v8, v16, s[38:39] sc1
	global_load_dword v9, v16, s[40:41] sc1
	global_load_dword v10, v16, s[42:43] sc1
	global_load_dword v11, v16, s[44:45] sc1
	global_load_dword v12, v16, s[46:47] sc1
	global_load_dword v13, v16, s[48:49] sc1
	global_load_dword v14, v16, s[50:51] sc1
	s_mov_b64 s[52:53], -1
	s_mov_b64 s[54:55], -1
	s_waitcnt vmcnt(14)
	v_add_u32_e32 v17, v0, v15
	s_waitcnt vmcnt(13)
	v_add_u32_e32 v17, v17, v1
	s_waitcnt vmcnt(12)
	v_add_u32_e32 v17, v17, v2
	s_waitcnt vmcnt(11)
	v_add_u32_e32 v17, v17, v3
	s_waitcnt vmcnt(10)
	v_add_u32_e32 v17, v17, v4
	s_waitcnt vmcnt(9)
	v_add_u32_e32 v17, v17, v5
	s_waitcnt vmcnt(8)
	v_add_u32_e32 v17, v17, v6
	s_waitcnt vmcnt(7)
	v_add_u32_e32 v17, v17, v7
	s_waitcnt vmcnt(6)
	v_add_u32_e32 v17, v17, v8
	s_waitcnt vmcnt(5)
	v_add_u32_e32 v17, v17, v9
	s_waitcnt vmcnt(4)
	v_add_u32_e32 v17, v17, v10
	s_waitcnt vmcnt(3)
	v_add_u32_e32 v17, v17, v11
	s_waitcnt vmcnt(2)
	v_add_u32_e32 v17, v17, v12
	s_waitcnt vmcnt(1)
	v_add_u32_e32 v17, v17, v13
	s_waitcnt vmcnt(0)
	v_add_u32_e32 v17, v17, v14
	v_cmp_eq_u32_e32 vcc, s3, v17
	s_cbranch_vccnz .LBB0_1549
	s_and_b32 s52, s11, 0xff
	s_cmp_eq_u32 s52, 0
	s_mov_b64 s[52:53], -1
	s_mov_b64 s[56:57], -1
	s_nop 0
	s_cbranch_scc1 .LBB0_1554
	s_and_b64 vcc, exec, s[56:57]
	s_cbranch_vccz .LBB0_1549

; __device__ __forceinline__ unsigned xb_ld(unsigned* p)              { return __hip_atomic_load(p, __ATOMIC_RELAXED, __HIP_MEMORY_SCOPE_AGENT); }
; #define XB_SPIN(cond, bar) do { unsigned _sp = 0; while (cond) { __builtin_amdgcn_s_sleep(1); \
;     if ((++_sp & 255u) == 0u) { if (xb_ld(&(bar)[XB_TMO])) break; if (_sp > XB_SPIN_CAP) { atomicAdd(&(bar)[XB_TMO], 1u); break; } } } } while (0)
; __device__ __forceinline__ void xcd_barrier(const XcdBarrier& b) {
;     ...
;             else XB_SPIN(xb_ld(&bar[XB_TOPGEN]) == tg, bar);
.LBB0_1568:
	s_and_b32 s11, s3, 0xff
	s_mov_b64 s[22:23], -1
	s_cmp_lg_u32 s11, 0
	s_mov_b64 s[26:27], -1
	s_nop 0
	s_cbranch_scc0 .LBB0_1571
	s_and_b64 vcc, exec, s[26:27]
	s_cbranch_vccz .LBB0_1567

; __device__ __forceinline__ unsigned xb_ld(unsigned* p)              { return __hip_atomic_load(p, __ATOMIC_RELAXED, __HIP_MEMORY_SCOPE_AGENT); }
; #define XB_SPIN(cond, bar) do { unsigned _sp = 0; while (cond) { __builtin_amdgcn_s_sleep(1); \
;     if ((++_sp & 255u) == 0u) { if (xb_ld(&(bar)[XB_TMO])) break; if (_sp > XB_SPIN_CAP) { atomicAdd(&(bar)[XB_TMO], 1u); break; } } } } while (0)
; __device__ __forceinline__ void xcd_barrier(const XcdBarrier& b) {
;     ...
;             XB_SPIN(xb_ld(&bar[XB_XGEN(b.x)]) == gen, bar);
.LBB0_1585:
	s_and_b32 s11, s3, 0xff
	s_cmp_lg_u32 s11, 0
	s_mov_b64 s[24:25], -1
	s_nop 0
	s_cbranch_scc0 .LBB0_1588
	s_mov_b64 s[26:27], -1
	s_and_b64 vcc, exec, s[24:25]
	s_cbranch_vccz .LBB0_1584
